# PROJ unit order: groups of 2 row tiles (per-XCD round = 2 rows x 16 cols) (run 1)
# speedup vs baseline: 1.0108x; 1.0012x over previous
;     __device__ bool next(int i, Unit& u) const { if (r0 + i >= r1) return false; return base.next(r0 + i, u); }
;     __device__ bool next(int i, Unit& u) const { const int L = i * G + c; if (L >= 256) return false; u.pm = L; u.pn = L >> 3; return true; }
;     __device__ bool next(int i, Unit& u) const {
;         const long L = (long)i * G + c; if (L >= nwg) return false;
;         int wgid = (int)L; { const int q = nwg / NXCD, r = nwg % NXCD, xcd = wgid % NXCD, off = wgid / NXCD; wgid = (xcd < r ? xcd * (q + 1) : r * (q + 1) + (xcd - r) * q) + off; }
;         const int nig = WGM * nN, gid = wgid / nig, fm = gid * WGM, gsz = (nM - fm) < WGM ? (nM - fm) : WGM;
;         u.pm = fm + ((wgid % nig) % gsz); u.pn = (wgid % nig) / gsz; return true;
.LBB0_240:
	v_readlane_b32 s8, v255, 3
	s_cmp_lt_i32 s8, 2
	s_cselect_b64 s[6:7], -1, 0
	s_and_b64 s[16:17], s[6:7], s[4:5]
	s_andn2_b64 vcc, exec, s[16:17]
	v_readlane_b32 s9, v255, 4
	v_readlane_b32 s10, v255, 5
	v_readlane_b32 s11, v255, 6
	s_cbranch_vccnz .LBB0_597
	v_readlane_b32 s2, v255, 9
	s_cmpk_lt_i32 s66, 0xa00
	v_mbcnt_lo_u32_b32 v0, -1, 0
	v_mbcnt_hi_u32_b32 v0, -1, v0
	s_cselect_b64 s[4:5], -1, 0
	v_add_u32_e32 v8, s2, v0
	s_cmpk_gt_i32 s66, 0x9ff
	s_cbranch_scc1 .LBB0_243
	s_ashr_i32 s2, s66, 31
	s_lshr_b32 s2, s2, 29
	s_add_i32 s2, s66, s2
	s_ashr_i32 s6, s2, 3
	s_and_b32 s2, s2, -8
	s_sub_i32 s2, s66, s2
	s_cmp_lt_i32 s2, 0
	s_movk_i32 s7, 0x141
	s_cselect_b32 s7, s7, 0x140
	s_mul_i32 s2, s2, s7
	s_add_i32 s2, s2, s6
	s_mul_hi_i32 s6, s2, 0x66666667
	s_lshr_b32 s7, s6, 31
	s_ashr_i32 s6, s6, 4
	s_add_i32 s6, s6, s7
	s_lshl_b32 s7, s6, 1
	s_mulk_i32 s6, 0x28
	s_sub_i32 s2, s2, s6
	s_and_b32 s9, s2, 1
	s_add_i32 s8, s7, s9
	s_lshr_b32 s6, s2, 1

;     __device__ bool next(int i, Unit& u) const { if (r0 + i >= r1) return false; return base.next(r0 + i, u); }
;     __device__ bool next(int i, Unit& u) const { const int L = i * G + c; if (L >= 256) return false; u.pm = L; u.pn = L >> 3; return true; }
;     __device__ bool next(int i, Unit& u) const {
;         const long L = (long)i * G + c; if (L >= nwg) return false;
;         int wgid = (int)L; { const int q = nwg / NXCD, r = nwg % NXCD, xcd = wgid % NXCD, off = wgid / NXCD; wgid = (xcd < r ? xcd * (q + 1) : r * (q + 1) + (xcd - r) * q) + off; }
;         const int nig = WGM * nN, gid = wgid / nig, fm = gid * WGM, gsz = (nM - fm) < WGM ? (nM - fm) : WGM;
;         u.pm = fm + ((wgid % nig) % gsz); u.pn = (wgid % nig) / gsz; return true;
.LBB0_249:
	s_add_i32 s77, s77, 1
	s_mul_i32 s2, s77, s64
	s_mul_hi_u32 s4, s77, s65
	s_add_i32 s4, s4, s2
	s_mul_i32 s2, s77, s65
	v_readlane_b32 s14, v255, 7
	v_readlane_b32 s15, v255, 8
	s_add_u32 s14, s2, s14
	s_addc_u32 s15, s4, s66
	v_cmp_gt_i64_e32 vcc, s[14:15], v[164:165]
	v_cmp_lt_i64_e64 s[4:5], s[14:15], v[162:163]
	s_cbranch_vccnz .LBB0_251
	s_ashr_i32 s2, s14, 31
	s_lshr_b32 s2, s2, 29
	s_add_i32 s2, s14, s2
	s_ashr_i32 s7, s2, 3
	s_and_b32 s2, s2, -8
	s_sub_i32 s2, s14, s2
	s_cmp_lt_i32 s2, 0
	s_movk_i32 s9, 0x141
	s_cselect_b32 s9, s9, 0x140
	s_mul_i32 s2, s2, s9
	s_add_i32 s2, s2, s7
	s_mul_hi_i32 s7, s2, 0x66666667
	s_lshr_b32 s9, s7, 31
	s_ashr_i32 s7, s7, 4
	s_add_i32 s7, s7, s9
	s_lshl_b32 s9, s7, 1
	s_mulk_i32 s7, 0x28
	s_sub_i32 s2, s2, s7
	s_lshr_b32 s38, s2, 1
	s_and_b32 s2, s2, 1
	s_add_i32 s44, s9, s2
